# FFN-up K-loop: A(0,0) LDS-DMA group moved from SP2(t) to SP1(t+1) (vmcnt 8/6/8/6); attention QK^T K-fragment ds_reads pipelined 4 deep
# speedup vs baseline: 1.0012x; 1.0012x over previous
.LBB0_567:
	s_barrier
	ds_read_b128 v[194:197], v238
	ds_read_b128 v[198:201], v239
	ds_read_b128 v[202:205], v238 offset:8192
	ds_read_b128 v[206:209], v239 offset:8192
	s_waitcnt lgkmcnt(3)
	v_mfma_f32_32x32x16_bf16 v[146:161], v[194:197], v[162:165], 0
	ds_read_b128 v[194:197], v240
	s_waitcnt lgkmcnt(3)
	v_mfma_f32_32x32x16_bf16 v[146:161], v[198:201], v[166:169], v[146:161]
	ds_read_b128 v[198:201], v240 offset:8192
	s_waitcnt lgkmcnt(3)
	v_mfma_f32_32x32x16_bf16 v[130:145], v[202:205], v[162:165], 0
	ds_read_b128 v[202:205], v241
	s_waitcnt lgkmcnt(3)
	v_mfma_f32_32x32x16_bf16 v[130:145], v[206:209], v[166:169], v[130:145]
	ds_read_b128 v[206:209], v241 offset:8192
	s_waitcnt lgkmcnt(3)
	v_mfma_f32_32x32x16_bf16 v[146:161], v[194:197], v[170:173], v[146:161]
	ds_read_b128 v[194:197], v242
	s_waitcnt lgkmcnt(3)
	v_mfma_f32_32x32x16_bf16 v[130:145], v[198:201], v[170:173], v[130:145]
	ds_read_b128 v[198:201], v242 offset:8192
	s_waitcnt lgkmcnt(3)
	v_mfma_f32_32x32x16_bf16 v[146:161], v[202:205], v[174:177], v[146:161]
	ds_read_b128 v[202:205], v243
	s_waitcnt lgkmcnt(3)
	v_mfma_f32_32x32x16_bf16 v[130:145], v[206:209], v[174:177], v[130:145]
	ds_read_b128 v[206:209], v243 offset:8192
	s_waitcnt lgkmcnt(3)
	v_mfma_f32_32x32x16_bf16 v[146:161], v[194:197], v[178:181], v[146:161]
	ds_read_b128 v[194:197], v244
	s_waitcnt lgkmcnt(3)
	v_mfma_f32_32x32x16_bf16 v[130:145], v[198:201], v[178:181], v[130:145]
	ds_read_b128 v[198:201], v244 offset:8192
	s_waitcnt lgkmcnt(3)
	v_mfma_f32_32x32x16_bf16 v[146:161], v[202:205], v[182:185], v[146:161]
	ds_read_b128 v[202:205], v245
	s_waitcnt lgkmcnt(3)
	v_mfma_f32_32x32x16_bf16 v[130:145], v[206:209], v[182:185], v[130:145]
	ds_read_b128 v[206:209], v245 offset:8192
	s_waitcnt lgkmcnt(3)
	v_mfma_f32_32x32x16_bf16 v[146:161], v[194:197], v[186:189], v[146:161]
	s_waitcnt lgkmcnt(2)
	v_mfma_f32_32x32x16_bf16 v[130:145], v[198:201], v[186:189], v[130:145]
	s_waitcnt lgkmcnt(1)
	v_mfma_f32_32x32x16_bf16 v[146:161], v[202:205], v[190:193], v[146:161]
	s_waitcnt lgkmcnt(0)
	v_mfma_f32_32x32x16_bf16 v[130:145], v[206:209], v[190:193], v[130:145]
	s_nop 9
	v_max_f32_e32 v194, v147, v147
	v_max_f32_e32 v195, v146, v146
	v_max_f32_e32 v194, v195, v194
	v_max3_f32 v194, v194, v148, v149
	v_max3_f32 v194, v194, v150, v151
	v_max3_f32 v194, v194, v152, v153
	v_max3_f32 v194, v194, v154, v155
	v_max3_f32 v194, v194, v156, v157
	v_max3_f32 v194, v194, v158, v159
	v_max3_f32 v194, v194, v160, v161
	v_max3_f32 v194, v194, v130, v131
	v_max3_f32 v194, v194, v132, v133
	v_max3_f32 v194, v194, v134, v135
	v_max3_f32 v194, v194, v136, v137
	v_max3_f32 v194, v194, v138, v139
	v_max3_f32 v194, v194, v140, v141
	v_max3_f32 v194, v194, v142, v143
	v_max3_f32 v194, v194, v144, v145
	v_mov_b32_e32 v195, v194
	s_nop 1
	v_permlane32_swap_b32_e32 v194, v195
	v_max_f32_e32 v195, v195, v195
	v_max_f32_e32 v194, v194, v194
	v_max_f32_e32 v194, v194, v195
	v_sub_f32_e32 v195, v194, v249
	v_cmp_ge_f32_e32 vcc, s55, v195
	v_max_f32_e32 v195, v249, v249
	v_max_f32_e32 v220, v195, v194
	v_sub_f32_e32 v194, v249, v220
	v_mul_f32_e32 v194, 0x3e0293ee, v194
	v_exp_f32_e32 v194, v194
	s_cmp_eq_u64 vcc, exec
	s_cselect_b64 s[6:7], -1, 0
	v_cndmask_b32_e64 v246, v194, 1.0, s[6:7]
	v_cmp_gt_f32_e32 vcc, 1.0, v246
	s_cbranch_vccz .LBB0_571
	s_and_saveexec_b64 s[0:1], s[4:5]
	ds_write_b32 v225, v246 offset:128
	s_or_b64 exec, exec, s[0:1]
	s_waitcnt lgkmcnt(0)
	v_add_u32_e32 v194, s65, v210
	ds_read_b128 v[206:209], v194 offset:224
	ds_read_b128 v[202:205], v194 offset:192
	ds_read_b128 v[198:201], v194 offset:160
	ds_read_b128 v[194:197], v194 offset:128
	s_waitcnt lgkmcnt(0)
	v_pk_mul_f32 v[14:15], v[14:15], v[206:207]
	s_waitcnt lgkmcnt(2)
	v_pk_mul_f32 v[10:11], v[10:11], v[202:203]
	s_waitcnt lgkmcnt(1)
	v_pk_mul_f32 v[6:7], v[6:7], v[198:199]
	v_pk_mul_f32 v[16:17], v[16:17], v[208:209]
	v_pk_mul_f32 v[12:13], v[12:13], v[204:205]
	v_pk_mul_f32 v[8:9], v[8:9], v[200:201]
	s_waitcnt lgkmcnt(0)
	v_pk_mul_f32 v[4:5], v[4:5], v[196:197]
	v_pk_mul_f32 v[2:3], v[2:3], v[194:195]
	v_pk_mul_f32 v[126:127], v[126:127], v[206:207]
	v_pk_mul_f32 v[122:123], v[122:123], v[202:203]
	v_pk_mul_f32 v[118:119], v[118:119], v[198:199]
	v_pk_mul_f32 v[128:129], v[128:129], v[208:209]
	v_pk_mul_f32 v[124:125], v[124:125], v[204:205]
	v_pk_mul_f32 v[120:121], v[120:121], v[200:201]
	v_pk_mul_f32 v[116:117], v[116:117], v[196:197]
	v_pk_mul_f32 v[114:115], v[114:115], v[194:195]
	v_pk_mul_f32 v[110:111], v[110:111], v[206:207]
	v_pk_mul_f32 v[106:107], v[106:107], v[202:203]
	v_pk_mul_f32 v[102:103], v[102:103], v[198:199]
	v_pk_mul_f32 v[112:113], v[112:113], v[208:209]
	v_pk_mul_f32 v[108:109], v[108:109], v[204:205]
	v_pk_mul_f32 v[104:105], v[104:105], v[200:201]
	v_pk_mul_f32 v[100:101], v[100:101], v[196:197]
	v_pk_mul_f32 v[98:99], v[98:99], v[194:195]
	v_pk_mul_f32 v[94:95], v[94:95], v[206:207]
	v_pk_mul_f32 v[90:91], v[90:91], v[202:203]
	v_pk_mul_f32 v[86:87], v[86:87], v[198:199]
	v_pk_mul_f32 v[96:97], v[96:97], v[208:209]
	v_pk_mul_f32 v[92:93], v[92:93], v[204:205]
	v_pk_mul_f32 v[88:89], v[88:89], v[200:201]
	v_pk_mul_f32 v[84:85], v[84:85], v[196:197]
	v_pk_mul_f32 v[82:83], v[82:83], v[194:195]
	v_pk_mul_f32 v[78:79], v[78:79], v[206:207]
	v_pk_mul_f32 v[74:75], v[74:75], v[202:203]
	v_pk_mul_f32 v[70:71], v[70:71], v[198:199]
	v_pk_mul_f32 v[80:81], v[80:81], v[208:209]
	v_pk_mul_f32 v[76:77], v[76:77], v[204:205]
	v_pk_mul_f32 v[72:73], v[72:73], v[200:201]
	v_pk_mul_f32 v[68:69], v[68:69], v[196:197]
	v_pk_mul_f32 v[66:67], v[66:67], v[194:195]
	v_pk_mul_f32 v[62:63], v[62:63], v[206:207]
	v_pk_mul_f32 v[58:59], v[58:59], v[202:203]
	v_pk_mul_f32 v[54:55], v[54:55], v[198:199]
	v_pk_mul_f32 v[64:65], v[64:65], v[208:209]
	v_pk_mul_f32 v[60:61], v[60:61], v[204:205]
	v_pk_mul_f32 v[56:57], v[56:57], v[200:201]
	v_pk_mul_f32 v[52:53], v[52:53], v[196:197]
	v_pk_mul_f32 v[50:51], v[50:51], v[194:195]
	v_pk_mul_f32 v[46:47], v[46:47], v[206:207]
	v_pk_mul_f32 v[42:43], v[42:43], v[202:203]
	v_pk_mul_f32 v[38:39], v[38:39], v[198:199]
	v_pk_mul_f32 v[48:49], v[48:49], v[208:209]
	v_pk_mul_f32 v[44:45], v[44:45], v[204:205]
	v_pk_mul_f32 v[40:41], v[40:41], v[200:201]
	v_pk_mul_f32 v[36:37], v[36:37], v[196:197]
	v_pk_mul_f32 v[34:35], v[34:35], v[194:195]
	v_pk_mul_f32 v[30:31], v[30:31], v[206:207]
	v_pk_mul_f32 v[26:27], v[26:27], v[202:203]
	v_pk_mul_f32 v[22:23], v[22:23], v[198:199]
	v_pk_mul_f32 v[32:33], v[32:33], v[208:209]
	v_pk_mul_f32 v[28:29], v[28:29], v[204:205]
	v_pk_mul_f32 v[24:25], v[24:25], v[200:201]
	v_pk_mul_f32 v[20:21], v[20:21], v[196:197]
	v_pk_mul_f32 v[18:19], v[18:19], v[194:195]

.LBB0_575:
	s_barrier
	ds_read_b128 v[194:197], v238 offset:16384
	ds_read_b128 v[198:201], v239 offset:16384
	ds_read_b128 v[202:205], v238 offset:24576
	ds_read_b128 v[206:209], v239 offset:24576
	s_waitcnt lgkmcnt(3)
	v_mfma_f32_32x32x16_bf16 v[146:161], v[194:197], v[162:165], 0
	ds_read_b128 v[194:197], v240 offset:16384
	s_waitcnt lgkmcnt(3)
	v_mfma_f32_32x32x16_bf16 v[146:161], v[198:201], v[166:169], v[146:161]
	ds_read_b128 v[198:201], v240 offset:24576
	s_waitcnt lgkmcnt(3)
	v_mfma_f32_32x32x16_bf16 v[130:145], v[202:205], v[162:165], 0
	ds_read_b128 v[202:205], v241 offset:16384
	s_waitcnt lgkmcnt(3)
	v_mfma_f32_32x32x16_bf16 v[130:145], v[206:209], v[166:169], v[130:145]
	ds_read_b128 v[206:209], v241 offset:24576
	s_waitcnt lgkmcnt(3)
	v_mfma_f32_32x32x16_bf16 v[146:161], v[194:197], v[170:173], v[146:161]
	ds_read_b128 v[194:197], v242 offset:16384
	s_waitcnt lgkmcnt(3)
	v_mfma_f32_32x32x16_bf16 v[130:145], v[198:201], v[170:173], v[130:145]
	ds_read_b128 v[198:201], v242 offset:24576
	s_waitcnt lgkmcnt(3)
	v_mfma_f32_32x32x16_bf16 v[146:161], v[202:205], v[174:177], v[146:161]
	ds_read_b128 v[202:205], v243 offset:16384
	s_waitcnt lgkmcnt(3)
	v_mfma_f32_32x32x16_bf16 v[130:145], v[206:209], v[174:177], v[130:145]
	ds_read_b128 v[206:209], v243 offset:24576
	s_waitcnt lgkmcnt(3)
	v_mfma_f32_32x32x16_bf16 v[146:161], v[194:197], v[178:181], v[146:161]
	ds_read_b128 v[194:197], v244 offset:16384
	s_waitcnt lgkmcnt(3)
	v_mfma_f32_32x32x16_bf16 v[130:145], v[198:201], v[178:181], v[130:145]
	ds_read_b128 v[198:201], v244 offset:24576
	s_waitcnt lgkmcnt(3)
	v_mfma_f32_32x32x16_bf16 v[146:161], v[202:205], v[182:185], v[146:161]
	ds_read_b128 v[202:205], v245 offset:16384
	s_waitcnt lgkmcnt(3)
	v_mfma_f32_32x32x16_bf16 v[130:145], v[206:209], v[182:185], v[130:145]
	ds_read_b128 v[206:209], v245 offset:24576
	s_waitcnt lgkmcnt(3)
	v_mfma_f32_32x32x16_bf16 v[146:161], v[194:197], v[186:189], v[146:161]
	s_waitcnt lgkmcnt(2)
	v_mfma_f32_32x32x16_bf16 v[130:145], v[198:201], v[186:189], v[130:145]
	s_waitcnt lgkmcnt(1)
	v_mfma_f32_32x32x16_bf16 v[146:161], v[202:205], v[190:193], v[146:161]
	s_waitcnt lgkmcnt(0)
	v_mfma_f32_32x32x16_bf16 v[130:145], v[206:209], v[190:193], v[130:145]
	s_nop 9
	v_max_f32_e32 v194, v147, v147
	v_max_f32_e32 v195, v146, v146
	v_max_f32_e32 v194, v195, v194
	v_max3_f32 v194, v194, v148, v149
	v_max3_f32 v194, v194, v150, v151
	v_max3_f32 v194, v194, v152, v153
	v_max3_f32 v194, v194, v154, v155
	v_max3_f32 v194, v194, v156, v157
	v_max3_f32 v194, v194, v158, v159
	v_max3_f32 v194, v194, v160, v161
	v_max3_f32 v194, v194, v130, v131
	v_max3_f32 v194, v194, v132, v133
	v_max3_f32 v194, v194, v134, v135
	v_max3_f32 v194, v194, v136, v137
	v_max3_f32 v194, v194, v138, v139
	v_max3_f32 v194, v194, v140, v141
	v_max3_f32 v194, v194, v142, v143
	v_max3_f32 v194, v194, v144, v145
	v_mov_b32_e32 v195, v194
	s_nop 1
	v_permlane32_swap_b32_e32 v194, v195
	v_max_f32_e32 v195, v195, v195
	v_max_f32_e32 v194, v194, v194
	v_max_f32_e32 v194, v194, v195
	v_sub_f32_e32 v195, v194, v249
	v_cmp_ge_f32_e32 vcc, s55, v195
	v_max_f32_e32 v195, v249, v249
	v_max_f32_e32 v251, v195, v194
	v_sub_f32_e32 v194, v249, v251
	v_mul_f32_e32 v194, 0x3e0293ee, v194
	v_exp_f32_e32 v194, v194
	s_cmp_eq_u64 vcc, exec
	s_cselect_b64 s[6:7], -1, 0
	v_cndmask_b32_e64 v250, v194, 1.0, s[6:7]
	v_cmp_gt_f32_e32 vcc, 1.0, v250
	s_cbranch_vccz .LBB0_579
	s_and_saveexec_b64 s[0:1], s[4:5]
	ds_write_b32 v225, v250 offset:128
	s_or_b64 exec, exec, s[0:1]
	s_waitcnt lgkmcnt(0)
	v_add_u32_e32 v194, s65, v210
	ds_read_b128 v[206:209], v194 offset:224
	ds_read_b128 v[202:205], v194 offset:192
	ds_read_b128 v[198:201], v194 offset:160
	ds_read_b128 v[194:197], v194 offset:128
	s_waitcnt lgkmcnt(0)
	v_pk_mul_f32 v[14:15], v[14:15], v[206:207]
	v_pk_mul_f32 v[10:11], v[10:11], v[202:203]
	v_pk_mul_f32 v[6:7], v[6:7], v[198:199]
	v_pk_mul_f32 v[16:17], v[16:17], v[208:209]
	v_pk_mul_f32 v[12:13], v[12:13], v[204:205]
	v_pk_mul_f32 v[8:9], v[8:9], v[200:201]
	v_pk_mul_f32 v[4:5], v[4:5], v[196:197]
	v_pk_mul_f32 v[2:3], v[2:3], v[194:195]
	v_pk_mul_f32 v[126:127], v[126:127], v[206:207]
	v_pk_mul_f32 v[122:123], v[122:123], v[202:203]
	v_pk_mul_f32 v[118:119], v[118:119], v[198:199]
	v_pk_mul_f32 v[128:129], v[128:129], v[208:209]
	v_pk_mul_f32 v[124:125], v[124:125], v[204:205]
	v_pk_mul_f32 v[120:121], v[120:121], v[200:201]
	v_pk_mul_f32 v[116:117], v[116:117], v[196:197]
	v_pk_mul_f32 v[114:115], v[114:115], v[194:195]
	v_pk_mul_f32 v[110:111], v[110:111], v[206:207]
	v_pk_mul_f32 v[106:107], v[106:107], v[202:203]
	v_pk_mul_f32 v[102:103], v[102:103], v[198:199]
	v_pk_mul_f32 v[112:113], v[112:113], v[208:209]
	v_pk_mul_f32 v[108:109], v[108:109], v[204:205]
	v_pk_mul_f32 v[104:105], v[104:105], v[200:201]
	v_pk_mul_f32 v[100:101], v[100:101], v[196:197]
	v_pk_mul_f32 v[98:99], v[98:99], v[194:195]
	v_pk_mul_f32 v[94:95], v[94:95], v[206:207]
	v_pk_mul_f32 v[90:91], v[90:91], v[202:203]
	v_pk_mul_f32 v[86:87], v[86:87], v[198:199]
	v_pk_mul_f32 v[96:97], v[96:97], v[208:209]
	v_pk_mul_f32 v[92:93], v[92:93], v[204:205]
	v_pk_mul_f32 v[88:89], v[88:89], v[200:201]
	v_pk_mul_f32 v[84:85], v[84:85], v[196:197]
	v_pk_mul_f32 v[82:83], v[82:83], v[194:195]
	v_pk_mul_f32 v[78:79], v[78:79], v[206:207]
	v_pk_mul_f32 v[74:75], v[74:75], v[202:203]
	v_pk_mul_f32 v[70:71], v[70:71], v[198:199]
	v_pk_mul_f32 v[80:81], v[80:81], v[208:209]
	v_pk_mul_f32 v[76:77], v[76:77], v[204:205]
	v_pk_mul_f32 v[72:73], v[72:73], v[200:201]
	v_pk_mul_f32 v[68:69], v[68:69], v[196:197]
	v_pk_mul_f32 v[66:67], v[66:67], v[194:195]
	v_pk_mul_f32 v[62:63], v[62:63], v[206:207]
	v_pk_mul_f32 v[58:59], v[58:59], v[202:203]
	v_pk_mul_f32 v[54:55], v[54:55], v[198:199]
	v_pk_mul_f32 v[64:65], v[64:65], v[208:209]
	v_pk_mul_f32 v[60:61], v[60:61], v[204:205]
	v_pk_mul_f32 v[56:57], v[56:57], v[200:201]
	v_pk_mul_f32 v[52:53], v[52:53], v[196:197]
	v_pk_mul_f32 v[50:51], v[50:51], v[194:195]
	v_pk_mul_f32 v[46:47], v[46:47], v[206:207]
	v_pk_mul_f32 v[42:43], v[42:43], v[202:203]
	v_pk_mul_f32 v[38:39], v[38:39], v[198:199]
	v_pk_mul_f32 v[48:49], v[48:49], v[208:209]
	v_pk_mul_f32 v[44:45], v[44:45], v[204:205]
	v_pk_mul_f32 v[40:41], v[40:41], v[200:201]
	v_pk_mul_f32 v[36:37], v[36:37], v[196:197]
	v_pk_mul_f32 v[34:35], v[34:35], v[194:195]
	v_pk_mul_f32 v[30:31], v[30:31], v[206:207]
	v_pk_mul_f32 v[26:27], v[26:27], v[202:203]
	v_pk_mul_f32 v[22:23], v[22:23], v[198:199]
	v_pk_mul_f32 v[32:33], v[32:33], v[208:209]
	v_pk_mul_f32 v[28:29], v[28:29], v[204:205]
	v_pk_mul_f32 v[24:25], v[24:25], v[200:201]
	v_pk_mul_f32 v[20:21], v[20:21], v[196:197]
	v_pk_mul_f32 v[18:19], v[18:19], v[194:195]

.LBB0_589:
	s_barrier
	ds_read_b128 v[194:197], v238
	ds_read_b128 v[198:201], v239
	ds_read_b128 v[202:205], v238 offset:8192
	ds_read_b128 v[206:209], v239 offset:8192
	s_waitcnt lgkmcnt(3)
	v_mfma_f32_32x32x16_bf16 v[146:161], v[194:197], v[162:165], 0
	ds_read_b128 v[194:197], v240
	s_waitcnt lgkmcnt(3)
	v_mfma_f32_32x32x16_bf16 v[146:161], v[198:201], v[166:169], v[146:161]
	ds_read_b128 v[198:201], v240 offset:8192
	s_waitcnt lgkmcnt(3)
	v_mfma_f32_32x32x16_bf16 v[130:145], v[202:205], v[162:165], 0
	ds_read_b128 v[202:205], v241
	s_waitcnt lgkmcnt(3)
	v_mfma_f32_32x32x16_bf16 v[130:145], v[206:209], v[166:169], v[130:145]
	ds_read_b128 v[206:209], v241 offset:8192
	s_waitcnt lgkmcnt(3)
	v_mfma_f32_32x32x16_bf16 v[146:161], v[194:197], v[170:173], v[146:161]
	ds_read_b128 v[194:197], v242
	s_waitcnt lgkmcnt(3)
	v_mfma_f32_32x32x16_bf16 v[130:145], v[198:201], v[170:173], v[130:145]
	ds_read_b128 v[198:201], v242 offset:8192
	s_waitcnt lgkmcnt(3)
	v_mfma_f32_32x32x16_bf16 v[146:161], v[202:205], v[174:177], v[146:161]
	ds_read_b128 v[202:205], v243
	s_waitcnt lgkmcnt(3)
	v_mfma_f32_32x32x16_bf16 v[130:145], v[206:209], v[174:177], v[130:145]
	ds_read_b128 v[206:209], v243 offset:8192
	s_waitcnt lgkmcnt(3)
	v_mfma_f32_32x32x16_bf16 v[146:161], v[194:197], v[178:181], v[146:161]
	ds_read_b128 v[194:197], v244
	s_waitcnt lgkmcnt(3)
	v_mfma_f32_32x32x16_bf16 v[130:145], v[198:201], v[178:181], v[130:145]
	ds_read_b128 v[198:201], v244 offset:8192
	s_waitcnt lgkmcnt(3)
	v_mfma_f32_32x32x16_bf16 v[146:161], v[202:205], v[182:185], v[146:161]
	ds_read_b128 v[202:205], v245
	s_waitcnt lgkmcnt(3)
	v_mfma_f32_32x32x16_bf16 v[130:145], v[206:209], v[182:185], v[130:145]
	ds_read_b128 v[206:209], v245 offset:8192
	s_waitcnt lgkmcnt(3)
	v_mfma_f32_32x32x16_bf16 v[146:161], v[194:197], v[186:189], v[146:161]
	s_waitcnt lgkmcnt(2)
	v_mfma_f32_32x32x16_bf16 v[130:145], v[198:201], v[186:189], v[130:145]
	s_waitcnt lgkmcnt(1)
	v_mfma_f32_32x32x16_bf16 v[146:161], v[202:205], v[190:193], v[146:161]
	s_waitcnt lgkmcnt(0)
	v_mfma_f32_32x32x16_bf16 v[130:145], v[206:209], v[190:193], v[130:145]
	s_nop 9
	v_max_f32_e32 v194, v147, v147
	v_max_f32_e32 v195, v146, v146
	v_max_f32_e32 v194, v195, v194
	v_max3_f32 v194, v194, v148, v149
	v_max3_f32 v194, v194, v150, v151
	v_max3_f32 v194, v194, v152, v153
	v_max3_f32 v194, v194, v154, v155
	v_max3_f32 v194, v194, v156, v157
	v_max3_f32 v194, v194, v158, v159
	v_max3_f32 v194, v194, v160, v161
	v_max3_f32 v194, v194, v130, v131
	v_max3_f32 v194, v194, v132, v133
	v_max3_f32 v194, v194, v134, v135
	v_max3_f32 v194, v194, v136, v137
	v_max3_f32 v194, v194, v138, v139
	v_max3_f32 v194, v194, v140, v141
	v_max3_f32 v194, v194, v142, v143
	v_max3_f32 v194, v194, v144, v145
	v_mov_b32_e32 v195, v194
	s_nop 1
	v_permlane32_swap_b32_e32 v194, v195
	v_max_f32_e32 v195, v195, v195
	v_max_f32_e32 v194, v194, v194
	v_max_f32_e32 v194, v194, v195
	v_sub_f32_e32 v195, v194, v249
	v_cmp_ge_f32_e32 vcc, s55, v195
	v_max_f32_e32 v195, v249, v249
	v_max_f32_e32 v220, v195, v194
	v_sub_f32_e32 v194, v249, v220
	v_mul_f32_e32 v194, 0x3e0293ee, v194
	v_exp_f32_e32 v194, v194
	s_cmp_eq_u64 vcc, exec
	s_cselect_b64 s[6:7], -1, 0
	v_cndmask_b32_e64 v246, v194, 1.0, s[6:7]
	v_cmp_gt_f32_e32 vcc, 1.0, v246
	s_cbranch_vccz .LBB0_593
	s_and_saveexec_b64 s[0:1], s[4:5]
	ds_write_b32 v225, v246 offset:128
	s_or_b64 exec, exec, s[0:1]
	s_waitcnt lgkmcnt(0)
	v_add_u32_e32 v194, s50, v210
	ds_read_b128 v[206:209], v194 offset:224
	ds_read_b128 v[202:205], v194 offset:192
	ds_read_b128 v[198:201], v194 offset:160
	ds_read_b128 v[194:197], v194 offset:128
	s_waitcnt lgkmcnt(0)
	v_pk_mul_f32 v[14:15], v[14:15], v[206:207]
	s_waitcnt lgkmcnt(2)
	v_pk_mul_f32 v[10:11], v[10:11], v[202:203]
	s_waitcnt lgkmcnt(1)
	v_pk_mul_f32 v[6:7], v[6:7], v[198:199]
	v_pk_mul_f32 v[16:17], v[16:17], v[208:209]
	v_pk_mul_f32 v[12:13], v[12:13], v[204:205]
	v_pk_mul_f32 v[8:9], v[8:9], v[200:201]
	s_waitcnt lgkmcnt(0)
	v_pk_mul_f32 v[4:5], v[4:5], v[196:197]
	v_pk_mul_f32 v[2:3], v[2:3], v[194:195]
	v_pk_mul_f32 v[30:31], v[30:31], v[206:207]
	v_pk_mul_f32 v[26:27], v[26:27], v[202:203]
	v_pk_mul_f32 v[22:23], v[22:23], v[198:199]
	v_pk_mul_f32 v[32:33], v[32:33], v[208:209]
	v_pk_mul_f32 v[28:29], v[28:29], v[204:205]
	v_pk_mul_f32 v[24:25], v[24:25], v[200:201]
	v_pk_mul_f32 v[20:21], v[20:21], v[196:197]
	v_pk_mul_f32 v[18:19], v[18:19], v[194:195]
	v_pk_mul_f32 v[46:47], v[46:47], v[206:207]
	v_pk_mul_f32 v[42:43], v[42:43], v[202:203]
	v_pk_mul_f32 v[38:39], v[38:39], v[198:199]
	v_pk_mul_f32 v[48:49], v[48:49], v[208:209]
	v_pk_mul_f32 v[44:45], v[44:45], v[204:205]
	v_pk_mul_f32 v[40:41], v[40:41], v[200:201]
	v_pk_mul_f32 v[36:37], v[36:37], v[196:197]
	v_pk_mul_f32 v[34:35], v[34:35], v[194:195]
	v_pk_mul_f32 v[62:63], v[62:63], v[206:207]
	v_pk_mul_f32 v[58:59], v[58:59], v[202:203]
	v_pk_mul_f32 v[54:55], v[54:55], v[198:199]
	v_pk_mul_f32 v[64:65], v[64:65], v[208:209]
	v_pk_mul_f32 v[60:61], v[60:61], v[204:205]
	v_pk_mul_f32 v[56:57], v[56:57], v[200:201]
	v_pk_mul_f32 v[52:53], v[52:53], v[196:197]
	v_pk_mul_f32 v[50:51], v[50:51], v[194:195]
	v_pk_mul_f32 v[78:79], v[78:79], v[206:207]
	v_pk_mul_f32 v[74:75], v[74:75], v[202:203]
	v_pk_mul_f32 v[70:71], v[70:71], v[198:199]
	v_pk_mul_f32 v[80:81], v[80:81], v[208:209]
	v_pk_mul_f32 v[76:77], v[76:77], v[204:205]
	v_pk_mul_f32 v[72:73], v[72:73], v[200:201]
	v_pk_mul_f32 v[68:69], v[68:69], v[196:197]
	v_pk_mul_f32 v[66:67], v[66:67], v[194:195]
	v_pk_mul_f32 v[94:95], v[94:95], v[206:207]
	v_pk_mul_f32 v[90:91], v[90:91], v[202:203]
	v_pk_mul_f32 v[86:87], v[86:87], v[198:199]
	v_pk_mul_f32 v[96:97], v[96:97], v[208:209]
	v_pk_mul_f32 v[92:93], v[92:93], v[204:205]
	v_pk_mul_f32 v[88:89], v[88:89], v[200:201]
	v_pk_mul_f32 v[84:85], v[84:85], v[196:197]
	v_pk_mul_f32 v[82:83], v[82:83], v[194:195]
	v_pk_mul_f32 v[110:111], v[110:111], v[206:207]
	v_pk_mul_f32 v[106:107], v[106:107], v[202:203]
	v_pk_mul_f32 v[102:103], v[102:103], v[198:199]
	v_pk_mul_f32 v[112:113], v[112:113], v[208:209]
	v_pk_mul_f32 v[108:109], v[108:109], v[204:205]
	v_pk_mul_f32 v[104:105], v[104:105], v[200:201]
	v_pk_mul_f32 v[100:101], v[100:101], v[196:197]
	v_pk_mul_f32 v[98:99], v[98:99], v[194:195]
	v_pk_mul_f32 v[126:127], v[126:127], v[206:207]
	v_pk_mul_f32 v[122:123], v[122:123], v[202:203]
	v_pk_mul_f32 v[118:119], v[118:119], v[198:199]
	v_pk_mul_f32 v[128:129], v[128:129], v[208:209]
	v_pk_mul_f32 v[124:125], v[124:125], v[204:205]
	v_pk_mul_f32 v[120:121], v[120:121], v[200:201]
	v_pk_mul_f32 v[116:117], v[116:117], v[196:197]
	v_pk_mul_f32 v[114:115], v[114:115], v[194:195]

.LBB0_597:
	s_barrier
	ds_read_b128 v[194:197], v238 offset:16384
	ds_read_b128 v[198:201], v239 offset:16384
	ds_read_b128 v[202:205], v238 offset:24576
	ds_read_b128 v[206:209], v239 offset:24576
	s_waitcnt lgkmcnt(3)
	v_mfma_f32_32x32x16_bf16 v[146:161], v[194:197], v[162:165], 0
	ds_read_b128 v[194:197], v240 offset:16384
	s_waitcnt lgkmcnt(3)
	v_mfma_f32_32x32x16_bf16 v[146:161], v[198:201], v[166:169], v[146:161]
	ds_read_b128 v[198:201], v240 offset:24576
	s_waitcnt lgkmcnt(3)
	v_mfma_f32_32x32x16_bf16 v[130:145], v[202:205], v[162:165], 0
	ds_read_b128 v[202:205], v241 offset:16384
	s_waitcnt lgkmcnt(3)
	v_mfma_f32_32x32x16_bf16 v[130:145], v[206:209], v[166:169], v[130:145]
	ds_read_b128 v[206:209], v241 offset:24576
	s_waitcnt lgkmcnt(3)
	v_mfma_f32_32x32x16_bf16 v[146:161], v[194:197], v[170:173], v[146:161]
	ds_read_b128 v[194:197], v242 offset:16384
	s_waitcnt lgkmcnt(3)
	v_mfma_f32_32x32x16_bf16 v[130:145], v[198:201], v[170:173], v[130:145]
	ds_read_b128 v[198:201], v242 offset:24576
	s_waitcnt lgkmcnt(3)
	v_mfma_f32_32x32x16_bf16 v[146:161], v[202:205], v[174:177], v[146:161]
	ds_read_b128 v[202:205], v243 offset:16384
	s_waitcnt lgkmcnt(3)
	v_mfma_f32_32x32x16_bf16 v[130:145], v[206:209], v[174:177], v[130:145]
	ds_read_b128 v[206:209], v243 offset:24576
	s_waitcnt lgkmcnt(3)
	v_mfma_f32_32x32x16_bf16 v[146:161], v[194:197], v[178:181], v[146:161]
	ds_read_b128 v[194:197], v244 offset:16384
	s_waitcnt lgkmcnt(3)
	v_mfma_f32_32x32x16_bf16 v[130:145], v[198:201], v[178:181], v[130:145]
	ds_read_b128 v[198:201], v244 offset:24576
	s_waitcnt lgkmcnt(3)
	v_mfma_f32_32x32x16_bf16 v[146:161], v[202:205], v[182:185], v[146:161]
	ds_read_b128 v[202:205], v245 offset:16384
	s_waitcnt lgkmcnt(3)
	v_mfma_f32_32x32x16_bf16 v[130:145], v[206:209], v[182:185], v[130:145]
	ds_read_b128 v[206:209], v245 offset:24576
	s_waitcnt lgkmcnt(3)
	v_mfma_f32_32x32x16_bf16 v[146:161], v[194:197], v[186:189], v[146:161]
	s_waitcnt lgkmcnt(2)
	v_mfma_f32_32x32x16_bf16 v[130:145], v[198:201], v[186:189], v[130:145]
	s_waitcnt lgkmcnt(1)
	v_mfma_f32_32x32x16_bf16 v[146:161], v[202:205], v[190:193], v[146:161]
	s_waitcnt lgkmcnt(0)
	v_mfma_f32_32x32x16_bf16 v[130:145], v[206:209], v[190:193], v[130:145]
	s_nop 9
	v_max_f32_e32 v194, v147, v147
	v_max_f32_e32 v195, v146, v146
	v_max_f32_e32 v194, v195, v194
	v_max3_f32 v194, v194, v148, v149
	v_max3_f32 v194, v194, v150, v151
	v_max3_f32 v194, v194, v152, v153
	v_max3_f32 v194, v194, v154, v155
	v_max3_f32 v194, v194, v156, v157
	v_max3_f32 v194, v194, v158, v159
	v_max3_f32 v194, v194, v160, v161
	v_max3_f32 v194, v194, v130, v131
	v_max3_f32 v194, v194, v132, v133
	v_max3_f32 v194, v194, v134, v135
	v_max3_f32 v194, v194, v136, v137
	v_max3_f32 v194, v194, v138, v139
	v_max3_f32 v194, v194, v140, v141
	v_max3_f32 v194, v194, v142, v143
	v_max3_f32 v194, v194, v144, v145
	v_mov_b32_e32 v195, v194
	s_nop 1
	v_permlane32_swap_b32_e32 v194, v195
	v_max_f32_e32 v195, v195, v195
	v_max_f32_e32 v194, v194, v194
	v_max_f32_e32 v194, v194, v195
	v_sub_f32_e32 v195, v194, v249
	v_cmp_ge_f32_e32 vcc, s55, v195
	v_max_f32_e32 v195, v249, v249
	v_max_f32_e32 v251, v195, v194
	v_sub_f32_e32 v194, v249, v251
	v_mul_f32_e32 v194, 0x3e0293ee, v194
	v_exp_f32_e32 v194, v194
	s_cmp_eq_u64 vcc, exec
	s_cselect_b64 s[6:7], -1, 0
	v_cndmask_b32_e64 v250, v194, 1.0, s[6:7]
	v_cmp_gt_f32_e32 vcc, 1.0, v250
	s_cbranch_vccz .LBB0_601
	s_and_saveexec_b64 s[0:1], s[4:5]
	ds_write_b32 v225, v250 offset:128
	s_or_b64 exec, exec, s[0:1]
	s_waitcnt lgkmcnt(0)
	v_add_u32_e32 v194, s50, v210
	ds_read_b128 v[206:209], v194 offset:224
	ds_read_b128 v[202:205], v194 offset:192
	ds_read_b128 v[198:201], v194 offset:160
	ds_read_b128 v[194:197], v194 offset:128
	s_waitcnt lgkmcnt(0)
	v_pk_mul_f32 v[14:15], v[14:15], v[206:207]
	v_pk_mul_f32 v[10:11], v[10:11], v[202:203]
	v_pk_mul_f32 v[6:7], v[6:7], v[198:199]
	v_pk_mul_f32 v[16:17], v[16:17], v[208:209]
	v_pk_mul_f32 v[12:13], v[12:13], v[204:205]
	v_pk_mul_f32 v[8:9], v[8:9], v[200:201]
	v_pk_mul_f32 v[4:5], v[4:5], v[196:197]
	v_pk_mul_f32 v[2:3], v[2:3], v[194:195]
	v_pk_mul_f32 v[30:31], v[30:31], v[206:207]
	v_pk_mul_f32 v[26:27], v[26:27], v[202:203]
	v_pk_mul_f32 v[22:23], v[22:23], v[198:199]
	v_pk_mul_f32 v[32:33], v[32:33], v[208:209]
	v_pk_mul_f32 v[28:29], v[28:29], v[204:205]
	v_pk_mul_f32 v[24:25], v[24:25], v[200:201]
	v_pk_mul_f32 v[20:21], v[20:21], v[196:197]
	v_pk_mul_f32 v[18:19], v[18:19], v[194:195]
	v_pk_mul_f32 v[46:47], v[46:47], v[206:207]
	v_pk_mul_f32 v[42:43], v[42:43], v[202:203]
	v_pk_mul_f32 v[38:39], v[38:39], v[198:199]
	v_pk_mul_f32 v[48:49], v[48:49], v[208:209]
	v_pk_mul_f32 v[44:45], v[44:45], v[204:205]
	v_pk_mul_f32 v[40:41], v[40:41], v[200:201]
	v_pk_mul_f32 v[36:37], v[36:37], v[196:197]
	v_pk_mul_f32 v[34:35], v[34:35], v[194:195]
	v_pk_mul_f32 v[62:63], v[62:63], v[206:207]
	v_pk_mul_f32 v[58:59], v[58:59], v[202:203]
	v_pk_mul_f32 v[54:55], v[54:55], v[198:199]
	v_pk_mul_f32 v[64:65], v[64:65], v[208:209]
	v_pk_mul_f32 v[60:61], v[60:61], v[204:205]
	v_pk_mul_f32 v[56:57], v[56:57], v[200:201]
	v_pk_mul_f32 v[52:53], v[52:53], v[196:197]
	v_pk_mul_f32 v[50:51], v[50:51], v[194:195]
	v_pk_mul_f32 v[78:79], v[78:79], v[206:207]
	v_pk_mul_f32 v[74:75], v[74:75], v[202:203]
	v_pk_mul_f32 v[70:71], v[70:71], v[198:199]
	v_pk_mul_f32 v[80:81], v[80:81], v[208:209]
	v_pk_mul_f32 v[76:77], v[76:77], v[204:205]
	v_pk_mul_f32 v[72:73], v[72:73], v[200:201]
	v_pk_mul_f32 v[68:69], v[68:69], v[196:197]
	v_pk_mul_f32 v[66:67], v[66:67], v[194:195]
	v_pk_mul_f32 v[94:95], v[94:95], v[206:207]
	v_pk_mul_f32 v[90:91], v[90:91], v[202:203]
	v_pk_mul_f32 v[86:87], v[86:87], v[198:199]
	v_pk_mul_f32 v[96:97], v[96:97], v[208:209]
	v_pk_mul_f32 v[92:93], v[92:93], v[204:205]
	v_pk_mul_f32 v[88:89], v[88:89], v[200:201]
	v_pk_mul_f32 v[84:85], v[84:85], v[196:197]
	v_pk_mul_f32 v[82:83], v[82:83], v[194:195]
	v_pk_mul_f32 v[110:111], v[110:111], v[206:207]
	v_pk_mul_f32 v[106:107], v[106:107], v[202:203]
	v_pk_mul_f32 v[102:103], v[102:103], v[198:199]
	v_pk_mul_f32 v[112:113], v[112:113], v[208:209]
	v_pk_mul_f32 v[108:109], v[108:109], v[204:205]
	v_pk_mul_f32 v[104:105], v[104:105], v[200:201]
	v_pk_mul_f32 v[100:101], v[100:101], v[196:197]
	v_pk_mul_f32 v[98:99], v[98:99], v[194:195]
	v_pk_mul_f32 v[126:127], v[126:127], v[206:207]
	v_pk_mul_f32 v[122:123], v[122:123], v[202:203]
	v_pk_mul_f32 v[118:119], v[118:119], v[198:199]
	v_pk_mul_f32 v[128:129], v[128:129], v[208:209]
	v_pk_mul_f32 v[124:125], v[124:125], v[204:205]
	v_pk_mul_f32 v[120:121], v[120:121], v[200:201]
	v_pk_mul_f32 v[116:117], v[116:117], v[196:197]
	v_pk_mul_f32 v[114:115], v[114:115], v[194:195]

.LBB0_854:
	s_add_u32 s67, s24, 0xfff80080
	s_addc_u32 s68, s25, -1
	s_and_b64 s[0:1], s[26:27], exec
	s_cselect_b32 s1, s57, s68
	s_cselect_b32 s0, s58, s67
	s_add_i32 s67, 0, 0x10000
	s_and_b64 s[26:27], s[26:27], exec
	s_cselect_b32 s27, s13, s61
	s_cselect_b32 s26, s59, s15
	s_add_i32 s72, 0, 0x14000
	v_add_u32_e32 v170, s67, v166
	v_add_u32_e32 v186, s72, v166
	ds_read_b128 v[134:137], v170
	ds_read_b128 v[138:141], v170 offset:1024
	ds_read_b128 v[142:145], v170 offset:2048
	ds_read_b128 v[170:173], v170 offset:3072
	ds_read_b128 v[174:177], v186
	ds_read_b128 v[178:181], v186 offset:1024
	ds_read_b128 v[182:185], v186 offset:2048
	ds_read_b128 v[186:189], v186 offset:3072
	v_lshl_add_u64 v[224:225], s[24:25], 0, v[162:163]
	s_add_i32 m0, s21, 0xc000
	ds_read_b128 v[190:193], v168
	ds_read_b128 v[194:197], v168 offset:1024
	ds_read_b128 v[198:201], v168 offset:2048
	ds_read_b128 v[202:205], v168 offset:3072
	ds_read_b128 v[206:209], v168 offset:4096
	ds_read_b128 v[216:219], v168 offset:5120
	ds_read_b128 v[220:223], v168 offset:6144
	ds_read_b128 v[234:237], v168 offset:7168
	global_load_lds_dwordx4 v[224:225], off
	v_lshl_add_u64 v[224:225], s[24:25], 0, v[164:165]
	s_add_i32 m0, s21, 0xe000
	s_nop 0
	global_load_lds_dwordx4 v[224:225], off
	s_waitcnt vmcnt(8)
	s_waitcnt lgkmcnt(0)
	s_barrier
	s_setprio 1
	s_waitcnt lgkmcnt(0)
	v_mfma_f32_16x16x32_bf16 v[126:129], v[134:137], v[190:193], v[126:129]
	v_mfma_f32_16x16x32_bf16 v[118:121], v[142:145], v[190:193], v[118:121]
	v_mfma_f32_16x16x32_bf16 v[110:113], v[134:137], v[198:201], v[110:113]
	v_mfma_f32_16x16x32_bf16 v[106:109], v[142:145], v[198:201], v[106:109]
	v_mfma_f32_16x16x32_bf16 v[94:97], v[134:137], v[206:209], v[94:97]
	v_mfma_f32_16x16x32_bf16 v[90:93], v[142:145], v[206:209], v[90:93]
	v_mfma_f32_16x16x32_bf16 v[78:81], v[134:137], v[220:223], v[78:81]
	v_mfma_f32_16x16x32_bf16 v[74:77], v[142:145], v[220:223], v[74:77]
	v_mfma_f32_16x16x32_bf16 v[126:129], v[138:141], v[194:197], v[126:129]
	v_mfma_f32_16x16x32_bf16 v[118:121], v[170:173], v[194:197], v[118:121]
	v_mfma_f32_16x16x32_bf16 v[110:113], v[138:141], v[202:205], v[110:113]
	v_mfma_f32_16x16x32_bf16 v[106:109], v[170:173], v[202:205], v[106:109]
	v_mfma_f32_16x16x32_bf16 v[94:97], v[138:141], v[216:219], v[94:97]
	v_mfma_f32_16x16x32_bf16 v[90:93], v[170:173], v[216:219], v[90:93]
	v_mfma_f32_16x16x32_bf16 v[78:81], v[138:141], v[234:237], v[78:81]
	v_mfma_f32_16x16x32_bf16 v[74:77], v[170:173], v[234:237], v[74:77]
	s_setprio 0
	s_setprio 1
	v_mfma_f32_16x16x32_bf16 v[122:125], v[174:177], v[190:193], v[122:125]
	v_mfma_f32_16x16x32_bf16 v[114:117], v[182:185], v[190:193], v[114:117]
	v_mfma_f32_16x16x32_bf16 v[102:105], v[174:177], v[198:201], v[102:105]
	v_mfma_f32_16x16x32_bf16 v[98:101], v[182:185], v[198:201], v[98:101]
	v_mfma_f32_16x16x32_bf16 v[86:89], v[174:177], v[206:209], v[86:89]
	v_mfma_f32_16x16x32_bf16 v[82:85], v[182:185], v[206:209], v[82:85]
	v_mfma_f32_16x16x32_bf16 v[70:73], v[174:177], v[220:223], v[70:73]
	v_mfma_f32_16x16x32_bf16 v[66:69], v[182:185], v[220:223], v[66:69]
	v_mfma_f32_16x16x32_bf16 v[122:125], v[178:181], v[194:197], v[122:125]
	v_mfma_f32_16x16x32_bf16 v[114:117], v[186:189], v[194:197], v[114:117]
	v_mfma_f32_16x16x32_bf16 v[102:105], v[178:181], v[202:205], v[102:105]
	v_mfma_f32_16x16x32_bf16 v[98:101], v[186:189], v[202:205], v[98:101]
	v_mfma_f32_16x16x32_bf16 v[86:89], v[178:181], v[216:219], v[86:89]
	v_mfma_f32_16x16x32_bf16 v[82:85], v[186:189], v[216:219], v[82:85]
	v_mfma_f32_16x16x32_bf16 v[70:73], v[178:181], v[234:237], v[70:73]
	v_mfma_f32_16x16x32_bf16 v[66:69], v[186:189], v[234:237], v[66:69]
	s_setprio 0
	s_barrier
	s_add_i32 s67, s67, s38
	v_lshl_add_u64 v[224:225], s[26:27], 0, v[152:153]
	s_mov_b32 m0, s67
	ds_read_b128 v[190:193], v168 offset:16384
	ds_read_b128 v[194:197], v168 offset:17408
	ds_read_b128 v[198:201], v168 offset:18432
	ds_read_b128 v[202:205], v168 offset:19456
	ds_read_b128 v[206:209], v168 offset:20480
	ds_read_b128 v[216:219], v168 offset:21504
	ds_read_b128 v[220:223], v168 offset:22528
	ds_read_b128 v[234:237], v168 offset:23552
	global_load_lds_dwordx4 v[224:225], off
	s_add_i32 m0, s67, 0x2000
	s_add_u32 s68, s26, 0x80000
	v_lshl_add_u64 v[238:239], s[26:27], 0, v[156:157]
	s_addc_u32 s69, s27, 0
	s_add_i32 s67, s72, s38
	global_load_lds_dwordx4 v[238:239], off
	v_lshl_add_u64 v[240:241], s[68:69], 0, v[152:153]
	s_mov_b32 m0, s67
	v_lshl_add_u64 v[242:243], s[0:1], 0, v[154:155]
	global_load_lds_dwordx4 v[240:241], off
	v_lshl_add_u64 v[240:241], s[68:69], 0, v[156:157]
	s_add_i32 m0, s67, 0x2000
	s_nop 0
	global_load_lds_dwordx4 v[240:241], off
	v_lshl_add_u64 v[240:241], s[0:1], 0, v[150:151]
	s_waitcnt vmcnt(6)
	s_waitcnt lgkmcnt(0)
	s_barrier
	s_setprio 1
	s_waitcnt lgkmcnt(0)
	v_mfma_f32_16x16x32_bf16 v[62:65], v[134:137], v[190:193], v[62:65]
	v_mfma_f32_16x16x32_bf16 v[58:61], v[142:145], v[190:193], v[58:61]
	v_mfma_f32_16x16x32_bf16 v[46:49], v[134:137], v[198:201], v[46:49]
	v_mfma_f32_16x16x32_bf16 v[42:45], v[142:145], v[198:201], v[42:45]
	v_mfma_f32_16x16x32_bf16 v[30:33], v[134:137], v[206:209], v[30:33]
	v_mfma_f32_16x16x32_bf16 v[26:29], v[142:145], v[206:209], v[26:29]
	v_mfma_f32_16x16x32_bf16 v[14:17], v[134:137], v[220:223], v[14:17]
	v_mfma_f32_16x16x32_bf16 v[10:13], v[142:145], v[220:223], v[10:13]
	v_mfma_f32_16x16x32_bf16 v[62:65], v[138:141], v[194:197], v[62:65]
	v_mfma_f32_16x16x32_bf16 v[58:61], v[170:173], v[194:197], v[58:61]
	v_mfma_f32_16x16x32_bf16 v[46:49], v[138:141], v[202:205], v[46:49]
	v_mfma_f32_16x16x32_bf16 v[42:45], v[170:173], v[202:205], v[42:45]
	v_mfma_f32_16x16x32_bf16 v[30:33], v[138:141], v[216:219], v[30:33]
	v_mfma_f32_16x16x32_bf16 v[26:29], v[170:173], v[216:219], v[26:29]
	v_mfma_f32_16x16x32_bf16 v[14:17], v[138:141], v[234:237], v[14:17]
	v_mfma_f32_16x16x32_bf16 v[10:13], v[170:173], v[234:237], v[10:13]
	s_setprio 0
	s_setprio 1
	v_mfma_f32_16x16x32_bf16 v[54:57], v[174:177], v[190:193], v[54:57]
	v_mfma_f32_16x16x32_bf16 v[50:53], v[182:185], v[190:193], v[50:53]
	v_mfma_f32_16x16x32_bf16 v[38:41], v[174:177], v[198:201], v[38:41]
	v_mfma_f32_16x16x32_bf16 v[34:37], v[182:185], v[198:201], v[34:37]
	v_mfma_f32_16x16x32_bf16 v[22:25], v[174:177], v[206:209], v[22:25]
	v_mfma_f32_16x16x32_bf16 v[18:21], v[182:185], v[206:209], v[18:21]
	v_mfma_f32_16x16x32_bf16 v[6:9], v[174:177], v[220:223], v[6:9]
	v_mfma_f32_16x16x32_bf16 v[2:5], v[182:185], v[220:223], v[2:5]
	v_mfma_f32_16x16x32_bf16 v[54:57], v[178:181], v[194:197], v[54:57]
	v_mfma_f32_16x16x32_bf16 v[50:53], v[186:189], v[194:197], v[50:53]
	v_mfma_f32_16x16x32_bf16 v[38:41], v[178:181], v[202:205], v[38:41]
	v_mfma_f32_16x16x32_bf16 v[34:37], v[186:189], v[202:205], v[34:37]
	v_mfma_f32_16x16x32_bf16 v[22:25], v[178:181], v[216:219], v[22:25]
	v_mfma_f32_16x16x32_bf16 v[18:21], v[186:189], v[216:219], v[18:21]
	v_mfma_f32_16x16x32_bf16 v[6:9], v[178:181], v[234:237], v[6:9]
	v_mfma_f32_16x16x32_bf16 v[2:5], v[186:189], v[234:237], v[2:5]
	s_setprio 0
	s_barrier
	s_add_i32 s67, 0, 0x18000
	s_add_i32 s68, 0, 0x1c000
	v_add_u32_e32 v170, s67, v166
	v_add_u32_e32 v186, s68, v166
	ds_read_b128 v[134:137], v170
	ds_read_b128 v[138:141], v170 offset:1024
	ds_read_b128 v[142:145], v170 offset:2048
	ds_read_b128 v[170:173], v170 offset:3072
	ds_read_b128 v[174:177], v186
	ds_read_b128 v[178:181], v186 offset:1024
	ds_read_b128 v[182:185], v186 offset:2048
	ds_read_b128 v[186:189], v186 offset:3072
	s_add_u32 s0, s0, 0x80000
	s_addc_u32 s1, s1, 0
	s_mov_b32 m0, s39
	v_lshl_add_u64 v[244:245], s[0:1], 0, v[150:151]
	ds_read_b128 v[190:193], v168 offset:32768
	ds_read_b128 v[194:197], v168 offset:33792
	ds_read_b128 v[198:201], v168 offset:34816
	ds_read_b128 v[202:205], v168 offset:35840
	ds_read_b128 v[206:209], v168 offset:36864
	ds_read_b128 v[216:219], v168 offset:37888
	ds_read_b128 v[220:223], v168 offset:38912
	ds_read_b128 v[234:237], v168 offset:39936
	global_load_lds_dwordx4 v[244:245], off
	v_lshl_add_u64 v[244:245], s[0:1], 0, v[154:155]
	s_mov_b32 m0, s40
	s_nop 0
	global_load_lds_dwordx4 v[244:245], off
	s_mov_b32 m0, s21
	s_nop 0
	global_load_lds_dwordx4 v[240:241], off
	s_mov_b32 m0, s23
	s_nop 0
	global_load_lds_dwordx4 v[242:243], off
	s_waitcnt vmcnt(8)
	s_waitcnt lgkmcnt(0)
	s_barrier
	s_setprio 1
	s_waitcnt lgkmcnt(0)
	v_mfma_f32_16x16x32_bf16 v[126:129], v[134:137], v[190:193], v[126:129]
	v_mfma_f32_16x16x32_bf16 v[118:121], v[142:145], v[190:193], v[118:121]
	v_mfma_f32_16x16x32_bf16 v[110:113], v[134:137], v[198:201], v[110:113]
	v_mfma_f32_16x16x32_bf16 v[106:109], v[142:145], v[198:201], v[106:109]
	v_mfma_f32_16x16x32_bf16 v[94:97], v[134:137], v[206:209], v[94:97]
	v_mfma_f32_16x16x32_bf16 v[90:93], v[142:145], v[206:209], v[90:93]
	v_mfma_f32_16x16x32_bf16 v[78:81], v[134:137], v[220:223], v[78:81]
	v_mfma_f32_16x16x32_bf16 v[74:77], v[142:145], v[220:223], v[74:77]
	v_mfma_f32_16x16x32_bf16 v[126:129], v[138:141], v[194:197], v[126:129]
	v_mfma_f32_16x16x32_bf16 v[118:121], v[170:173], v[194:197], v[118:121]
	v_mfma_f32_16x16x32_bf16 v[110:113], v[138:141], v[202:205], v[110:113]
	v_mfma_f32_16x16x32_bf16 v[106:109], v[170:173], v[202:205], v[106:109]
	v_mfma_f32_16x16x32_bf16 v[94:97], v[138:141], v[216:219], v[94:97]
	v_mfma_f32_16x16x32_bf16 v[90:93], v[170:173], v[216:219], v[90:93]
	v_mfma_f32_16x16x32_bf16 v[78:81], v[138:141], v[234:237], v[78:81]
	v_mfma_f32_16x16x32_bf16 v[74:77], v[170:173], v[234:237], v[74:77]
	s_setprio 0
	s_setprio 1
	v_mfma_f32_16x16x32_bf16 v[122:125], v[174:177], v[190:193], v[122:125]
	v_mfma_f32_16x16x32_bf16 v[114:117], v[182:185], v[190:193], v[114:117]
	v_mfma_f32_16x16x32_bf16 v[102:105], v[174:177], v[198:201], v[102:105]
	v_mfma_f32_16x16x32_bf16 v[98:101], v[182:185], v[198:201], v[98:101]
	v_mfma_f32_16x16x32_bf16 v[86:89], v[174:177], v[206:209], v[86:89]
	v_mfma_f32_16x16x32_bf16 v[82:85], v[182:185], v[206:209], v[82:85]
	v_mfma_f32_16x16x32_bf16 v[70:73], v[174:177], v[220:223], v[70:73]
	v_mfma_f32_16x16x32_bf16 v[66:69], v[182:185], v[220:223], v[66:69]
	v_mfma_f32_16x16x32_bf16 v[122:125], v[178:181], v[194:197], v[122:125]
	v_mfma_f32_16x16x32_bf16 v[114:117], v[186:189], v[194:197], v[114:117]
	v_mfma_f32_16x16x32_bf16 v[102:105], v[178:181], v[202:205], v[102:105]
	v_mfma_f32_16x16x32_bf16 v[98:101], v[186:189], v[202:205], v[98:101]
	v_mfma_f32_16x16x32_bf16 v[86:89], v[178:181], v[216:219], v[86:89]
	v_mfma_f32_16x16x32_bf16 v[82:85], v[186:189], v[216:219], v[82:85]
	v_mfma_f32_16x16x32_bf16 v[70:73], v[178:181], v[234:237], v[70:73]
	v_mfma_f32_16x16x32_bf16 v[66:69], v[186:189], v[234:237], v[66:69]
	s_setprio 0
	s_barrier
	s_add_i32 s0, s67, s38
	v_lshl_add_u64 v[224:225], v[224:225], 0, s[48:49]
	s_mov_b32 m0, s0
	ds_read_b128 v[190:193], v168 offset:49152
	ds_read_b128 v[194:197], v168 offset:50176
	ds_read_b128 v[198:201], v168 offset:51200
	ds_read_b128 v[202:205], v168 offset:52224
	ds_read_b128 v[206:209], v168 offset:53248
	ds_read_b128 v[216:219], v168 offset:54272
	ds_read_b128 v[220:223], v168 offset:55296
	ds_read_b128 v[234:237], v168 offset:56320
	global_load_lds_dwordx4 v[224:225], off
	s_add_i32 m0, s0, 0x2000
	s_add_u32 s0, s26, 0x80080
	v_lshl_add_u64 v[224:225], v[238:239], 0, s[48:49]
	s_addc_u32 s1, s27, 0
	s_add_i32 s26, s68, s38
	global_load_lds_dwordx4 v[224:225], off
	v_lshl_add_u64 v[224:225], s[0:1], 0, v[152:153]
	s_mov_b32 m0, s26
	s_nop 0
	global_load_lds_dwordx4 v[224:225], off
	v_lshl_add_u64 v[224:225], s[0:1], 0, v[156:157]
	s_add_i32 m0, s26, 0x2000
	s_nop 0
	global_load_lds_dwordx4 v[224:225], off
	v_lshl_add_u64 v[224:225], v[240:241], 0, s[48:49]
	s_mov_b32 m0, s42
	s_nop 0
	global_load_lds_dwordx4 v[224:225], off
	v_lshl_add_u64 v[224:225], v[242:243], 0, s[48:49]
	s_mov_b32 m0, s43
	s_nop 0
	global_load_lds_dwordx4 v[224:225], off
	s_waitcnt vmcnt(6)
	s_waitcnt lgkmcnt(0)
	s_barrier
	s_setprio 1
	s_waitcnt lgkmcnt(0)
	v_mfma_f32_16x16x32_bf16 v[62:65], v[134:137], v[190:193], v[62:65]
	v_mfma_f32_16x16x32_bf16 v[58:61], v[142:145], v[190:193], v[58:61]
	v_mfma_f32_16x16x32_bf16 v[46:49], v[134:137], v[198:201], v[46:49]
	v_mfma_f32_16x16x32_bf16 v[42:45], v[142:145], v[198:201], v[42:45]
	v_mfma_f32_16x16x32_bf16 v[30:33], v[134:137], v[206:209], v[30:33]
	v_mfma_f32_16x16x32_bf16 v[26:29], v[142:145], v[206:209], v[26:29]
	v_mfma_f32_16x16x32_bf16 v[14:17], v[134:137], v[220:223], v[14:17]
	v_mfma_f32_16x16x32_bf16 v[10:13], v[142:145], v[220:223], v[10:13]
	v_mfma_f32_16x16x32_bf16 v[62:65], v[138:141], v[194:197], v[62:65]
	v_mfma_f32_16x16x32_bf16 v[58:61], v[170:173], v[194:197], v[58:61]
	v_mfma_f32_16x16x32_bf16 v[46:49], v[138:141], v[202:205], v[46:49]
	v_mfma_f32_16x16x32_bf16 v[42:45], v[170:173], v[202:205], v[42:45]
	v_mfma_f32_16x16x32_bf16 v[30:33], v[138:141], v[216:219], v[30:33]
	v_mfma_f32_16x16x32_bf16 v[26:29], v[170:173], v[216:219], v[26:29]
	v_mfma_f32_16x16x32_bf16 v[14:17], v[138:141], v[234:237], v[14:17]
	v_mfma_f32_16x16x32_bf16 v[10:13], v[170:173], v[234:237], v[10:13]
	s_setprio 0
	s_setprio 1
	v_mfma_f32_16x16x32_bf16 v[54:57], v[174:177], v[190:193], v[54:57]
	v_mfma_f32_16x16x32_bf16 v[50:53], v[182:185], v[190:193], v[50:53]
	v_mfma_f32_16x16x32_bf16 v[38:41], v[174:177], v[198:201], v[38:41]
	v_mfma_f32_16x16x32_bf16 v[34:37], v[182:185], v[198:201], v[34:37]
	v_mfma_f32_16x16x32_bf16 v[22:25], v[174:177], v[206:209], v[22:25]
	v_mfma_f32_16x16x32_bf16 v[18:21], v[182:185], v[206:209], v[18:21]
	v_mfma_f32_16x16x32_bf16 v[6:9], v[174:177], v[220:223], v[6:9]
	v_mfma_f32_16x16x32_bf16 v[2:5], v[182:185], v[220:223], v[2:5]
	v_mfma_f32_16x16x32_bf16 v[54:57], v[178:181], v[194:197], v[54:57]
	v_mfma_f32_16x16x32_bf16 v[50:53], v[186:189], v[194:197], v[50:53]
	v_mfma_f32_16x16x32_bf16 v[38:41], v[178:181], v[202:205], v[38:41]
	v_mfma_f32_16x16x32_bf16 v[34:37], v[186:189], v[202:205], v[34:37]
	v_mfma_f32_16x16x32_bf16 v[22:25], v[178:181], v[216:219], v[22:25]
	v_mfma_f32_16x16x32_bf16 v[18:21], v[186:189], v[216:219], v[18:21]
	v_mfma_f32_16x16x32_bf16 v[6:9], v[178:181], v[234:237], v[6:9]
	v_mfma_f32_16x16x32_bf16 v[2:5], v[186:189], v[234:237], v[2:5]
	s_setprio 0
	s_barrier
	s_add_i32 s65, s65, 2
	s_add_u32 s24, s24, 0x100
	s_addc_u32 s25, s25, 0
	s_add_u32 s15, s15, 0x100
	s_addc_u32 s61, s61, 0
	s_cmp_gt_u32 s65, 29
	s_cbranch_scc1 .LBB0_857
